# static s_setprio 1 for waves 4-7 in the scan loop and the attention phase
# baseline (speedup 1.0000x reference)
.LBB0_349:
	s_or_b64 exec, exec, s[0:1]
	s_ashr_i32 s0, s2, 4
	s_ashr_i32 s1, s0, 31
	s_waitcnt vmcnt(0)
	v_lshrrev_b32_e32 v13, 3, v143
	s_lshl_b64 s[0:1], s[0:1], 23
	s_ashr_i32 s3, s2, 31
	v_lshl_or_b32 v130, v13, 12, s0
	v_mov_b32_e32 v131, s1
	v_lshl_add_u64 v[2:3], s[4:5], 0, v[130:131]
	s_mov_b32 s1, 0
	s_lshl_b32 s0, s30, 1
	s_lshl_b64 s[10:11], s[2:3], 19
	v_lshl_add_u64 v[2:3], v[2:3], 0, s[0:1]
	s_add_u32 s0, s97, s10
	s_addc_u32 s1, s33, s11
	v_mov_b32_e32 v11, 0
	s_add_u32 s4, s70, s10
	v_lshlrev_b32_e32 v134, 4, v143
	s_addc_u32 s5, s71, s11
	v_mov_b32_e32 v135, v11
	v_lshl_add_u64 v[4:5], s[4:5], 0, v[134:135]
	s_mov_b32 s4, 0xe000000
	v_and_b32_e32 v38, 7, v143
	v_add_co_u32_e32 v6, vcc, s4, v4
	v_lshlrev_b32_e32 v10, 5, v38
	s_nop 0
	v_addc_co_u32_e32 v7, vcc, 0, v5, vcc
	s_brev_b32 s4, 8
	v_lshl_add_u64 v[2:3], v[2:3], 0, v[10:11]
	v_add_co_u32_e32 v8, vcc, s4, v4
	global_load_dwordx4 v[14:17], v[2:3], off offset:16
	global_load_dwordx4 v[26:29], v[2:3], off
	v_lshl_add_u64 v[2:3], s[0:1], 0, v[134:135]
	v_addc_co_u32_e32 v9, vcc, 0, v5, vcc
	s_movk_i32 s4, 0x2000
	v_add_co_u32_e32 v2, vcc, s4, v2
	s_mov_b32 s4, 0xe002000
	s_nop 0
	v_addc_co_u32_e32 v3, vcc, 0, v3, vcc
	global_load_dwordx4 v[18:21], v[6:7], off
	global_load_dwordx4 v[22:25], v[8:9], off
	v_add_co_u32_e32 v6, vcc, s4, v4
	s_mov_b32 s4, 0x10002000
	s_nop 0
	v_addc_co_u32_e32 v7, vcc, 0, v5, vcc
	s_lshl_b64 s[22:23], s[2:3], 15
	global_load_dwordx4 v[30:33], v[2:3], off
	global_load_dwordx4 v[66:69], v[6:7], off
	v_add_co_u32_e32 v2, vcc, s4, v4
	s_add_u32 s4, s70, s22
	s_nop 0
	v_addc_co_u32_e32 v3, vcc, 0, v5, vcc
	s_addc_u32 s5, s71, s23
	v_lshlrev_b32_e32 v4, 4, v142
	v_mov_b32_e32 v5, v11
	v_lshl_add_u64 v[6:7], s[4:5], 0, v[4:5]
	s_mov_b32 s4, 0x17200000
	s_lshl_b64 s[24:25], s[2:3], 17
	v_add_co_u32_e32 v6, vcc, s4, v6
	s_add_u32 s4, s50, s24
	s_nop 0
	v_addc_co_u32_e32 v7, vcc, 0, v7, vcc
	global_load_dwordx4 v[78:81], v[2:3], off
	global_load_dwordx4 v[74:77], v[6:7], off
	s_addc_u32 s5, s51, s25
	v_and_b32_e32 v2, 0xff0, v134
	global_load_dwordx4 v[34:37], v134, s[0:1]
	global_load_dwordx4 v[70:73], v2, s[4:5]
	v_and_b32_e32 v1, 0xf0, v134
	s_lshr_b32 s12, s12, 2
	v_and_b32_e32 v12, 15, v143
	v_add_u32_e32 v5, 0, v1
	v_and_b32_e32 v1, 0x70, v134
	s_and_b32 s12, s12, 0x3ffffff0
	v_add_u32_e32 v6, 0, v1
	v_or_b32_e32 v1, s12, v12
	s_movk_i32 s13, 0x90
	v_lshrrev_b32_e32 v133, 4, v142
	v_mul_lo_u32 v3, v1, s13
	v_add_u32_e32 v161, 0, v3
	v_lshlrev_b32_e32 v3, 2, v133
	v_or_b32_e32 v7, s12, v3
	s_add_i32 s12, 0, 0x11c00
	s_movk_i32 s13, 0x210
	v_mov_b32_e32 v8, s12
	v_or_b32_e32 v42, 32, v12
	v_mad_u32_u24 v9, v13, s13, v8
	v_add_u32_e32 v39, 0x200, v143
	v_mul_u32_u24_e32 v41, 0x110, v12
	v_mul_u32_u24_e32 v167, 0x90, v12
	v_or_b32_e32 v153, 16, v3
	v_or_b32_e32 v152, 32, v3
	v_or_b32_e32 v151, 48, v3
	v_or_b32_e32 v150, 64, v3
	v_or_b32_e32 v149, 0x50, v3
	v_or_b32_e32 v148, 0x60, v3
	v_or_b32_e32 v135, 0x70, v3
	v_mad_u32_u24 v12, v12, s13, v8
	v_mad_u32_u24 v8, v42, s13, v8
	v_or_b32_e32 v2, s24, v2
	v_mov_b32_e32 v3, s25
	s_mov_b64 s[12:13], 0x16a01000
	v_lshlrev_b32_e32 v132, 4, v38
	v_lshlrev_b32_e32 v163, 3, v133
	v_lshlrev_b32_e32 v165, 6, v38
	v_lshrrev_b32_e32 v38, 4, v143
	v_lshrrev_b32_e32 v40, 4, v39
	v_lshrrev_b32_e32 v39, 3, v39
	v_lshlrev_b32_e32 v175, 1, v152
	v_lshl_add_u64 v[136:137], v[2:3], 0, s[12:13]
	v_or_b32_e32 v2, s22, v4
	v_mov_b32_e32 v3, s23
	s_mov_b64 s[12:13], 0x17200400
	v_or_b32_e32 v140, s10, v134
	s_and_b32 s10, s2, 15
	s_movk_i32 s0, 0x100
	v_add_u32_e32 v164, 0, v163
	v_lshlrev_b32_e32 v7, 2, v7
	v_mul_u32_u24_e32 v38, 0x110, v38
	v_mul_u32_u24_e32 v13, 0x90, v13
	v_mul_u32_u24_e32 v40, 0x110, v40
	v_mul_u32_u24_e32 v39, 0x90, v39
	v_mul_u32_u24_e32 v43, 0x110, v42
	v_add_u32_e32 v44, 0, v175
	v_lshl_add_u64 v[138:139], v[2:3], 0, s[12:13]
	s_lshl_b32 s10, s10, 8
	v_mbcnt_lo_u32_b32 v2, -1, 0
	v_cmp_gt_u32_e64 s[4:5], 64, v143
	v_cmp_gt_u32_e64 s[0:1], s0, v143
	v_lshlrev_b32_e32 v162, 3, v142
	v_and_b32_e32 v166, 48, v143
	v_lshlrev_b32_e32 v168, 2, v153
	v_lshlrev_b32_e32 v169, 2, v152
	v_lshlrev_b32_e32 v170, 2, v151
	v_lshlrev_b32_e32 v171, 2, v150
	v_lshlrev_b32_e32 v172, 2, v149
	v_lshlrev_b32_e32 v173, 2, v148
	v_lshlrev_b32_e32 v174, 2, v135
	v_mov_b32_e32 v141, s11
	v_or3_b32 v144, v130, s10, v10
	v_mov_b32_e32 v145, v131
	s_mov_b32 s31, 31
	s_mov_b64 s[10:11], 0x1ae40000
	s_add_i32 s34, 0, 0x11a00
	v_mbcnt_hi_u32_b32 v177, -1, v2
	v_mov_b32_e32 v178, 0x358637bd
	s_mov_b32 s35, 0x800000
	s_mov_b32 s36, 0x12600000
	s_mov_b64 s[12:13], 0x1000
	s_mov_b64 s[22:23], 0x400
	s_mov_b64 s[24:25], 0x4000
	s_mov_b64 s[26:27], 0x40000
	v_add_u32_e32 v182, v5, v38
	v_add_u32_e32 v180, v6, v13
	v_add_u32_e32 v181, v5, v40
	v_add_u32_e32 v179, v6, v39
	v_add_u32_e32 v157, v164, v41
	v_add_u32_e32 v159, v12, v7
	v_add_u32_e32 v158, v164, v43
	v_add_u32_e32 v156, v44, v167
	v_add_u32_e32 v155, v8, v7
	v_add_u32_e32 v154, v9, v165
	v_mov_b32_e32 v10, v11
	v_mov_b32_e32 v12, v11
	v_mov_b32_e32 v13, v11
	v_mov_b32_e32 v38, v11
	v_mov_b32_e32 v39, v11
	v_mov_b32_e32 v40, v11
	v_mov_b32_e32 v41, v11
	v_mov_b32_e32 v42, v11
	v_mov_b32_e32 v43, v11
	v_mov_b32_e32 v44, v11
	v_mov_b32_e32 v45, v11
	v_mov_b32_e32 v46, v11
	v_mov_b32_e32 v47, v11
	v_mov_b32_e32 v48, v11
	v_mov_b32_e32 v49, v11
	v_mov_b32_e32 v50, v11
	v_mov_b32_e32 v51, v11
	v_mov_b32_e32 v52, v11
	v_mov_b32_e32 v53, v11
	v_mov_b32_e32 v54, v11
	v_mov_b32_e32 v55, v11
	v_mov_b32_e32 v56, v11
	v_mov_b32_e32 v57, v11
	v_mov_b32_e32 v62, v11
	v_mov_b32_e32 v63, v11
	v_mov_b32_e32 v64, v11
	v_mov_b32_e32 v65, v11
	v_mov_b32_e32 v58, v11
	v_mov_b32_e32 v59, v11
	v_mov_b32_e32 v60, v11
	v_mov_b32_e32 v61, v11
	v_readfirstlane_b32 s98, v143
	s_lshr_b32 s98, s98, 8
	s_cmp_lg_u32 s98, 0
	s_cbranch_scc0 .Lprio_scan_done
	s_setprio 1
.Lprio_scan_done:
.LBB0_350:
	v_add_u32_e32 v185, 0, v134
	s_waitcnt vmcnt(1)
	v_readfirstlane_b32 vcc_lo, v236
	s_mov_b32 vcc_hi, 0
	s_cmp_lg_u32 vcc_lo, 0
	s_cbranch_scc1 .Lscan_fok

.LBB0_356:
	s_setprio 0
	s_waitcnt vmcnt(9)
	ds_write_b128 v182, v[34:37]
	s_waitcnt vmcnt(8)
	ds_write_b128 v180, v[18:21] offset:34816
	s_waitcnt vmcnt(7)
	ds_write_b128 v180, v[22:25] offset:53248
	s_waitcnt vmcnt(6)
	ds_write_b128 v181, v[30:33]
	s_waitcnt vmcnt(5)
	ds_write_b128 v179, v[66:69] offset:34816
	s_waitcnt vmcnt(4)
	ds_write_b128 v179, v[78:81] offset:53248
	s_and_saveexec_b64 s[10:11], s[4:5]
	s_cbranch_execz .LBB0_358
	v_add_u32_e32 v14, 0x11800, v185
	s_waitcnt vmcnt(3)
	ds_write_b128 v14, v[74:77]

.LBB0_1110:
	s_cmp_lt_i32 s72, 11
	s_cselect_b64 s[4:5], -1, 0
	s_and_b64 s[56:57], s[4:5], s[0:1]
	s_xor_b64 s[0:1], s[56:57], -1
	s_cmpk_gt_i32 s2, 0x2ff
	s_cselect_b64 s[4:5], -1, 0
	s_or_b64 s[0:1], s[0:1], s[4:5]
	s_and_b64 vcc, exec, s[0:1]
	s_cbranch_vccnz .LBB0_1179
	s_waitcnt vmcnt(0)
	v_lshrrev_b32_e32 v4, 8, v143
	v_lshlrev_b32_e32 v22, 3, v4
	v_mul_u32_u24_e32 v31, 0x1080, v4
	v_add_u32_e32 v4, 0x200, v143
	v_lshrrev_b32_e32 v33, 3, v4
	v_lshrrev_b32_e32 v4, 8, v4
	v_bfe_u32 v2, v143, 4, 2
	v_lshlrev_b32_e32 v24, 3, v4
	v_mul_u32_u24_e32 v43, 0x1080, v4
	v_or_b32_e32 v4, 0x400, v143
	s_movk_i32 s14, 0x420
	s_movk_i32 s16, 0x500
	v_lshrrev_b32_e32 v44, 3, v4
	v_cmp_gt_u32_e64 s[14:15], s14, v4
	v_cmp_gt_u32_e64 s[16:17], s16, v4
	v_lshrrev_b32_e32 v4, 8, v4
	v_lshlrev_b32_e32 v32, 2, v2
	v_and_b32_e32 v1, 15, v143
	v_lshlrev_b32_e32 v26, 3, v4
	v_mul_u32_u24_e32 v46, 0x1080, v4
	v_add_u32_e32 v4, 0x600, v143
	v_or_b32_e32 v7, 2, v32
	v_min_u32_e32 v3, 3, v1
	v_lshlrev_b32_e32 v18, 3, v2
	v_lshrrev_b32_e32 v5, 8, v4
	v_lshl_add_u32 v30, v2, 4, 0
	v_cmp_gt_u32_e64 s[24:25], v7, v1
	v_or_b32_e32 v7, 3, v32
	v_or_b32_e32 v21, 0x2000, v3
	v_and_b32_e32 v3, 7, v143
	v_and_b32_e32 v23, 0xff, v143
	s_movk_i32 s3, 0x7f
	v_lshrrev_b32_e32 v29, 3, v143
	v_lshlrev_b32_e32 v28, 3, v5
	v_mul_u32_u24_e32 v47, 0x1080, v5
	v_sub_u32_e32 v2, v30, v18
	v_lshrrev_b32_e32 v48, 3, v4
	v_or_b32_e32 v5, 0x80, v1
	v_cmp_gt_u32_e64 s[26:27], v7, v1
	v_or_b32_e32 v7, 0x82, v32
	s_movk_i32 s34, 0x210
	v_mov_b32_e32 v19, 0
	s_movk_i32 s0, 0xa0
	v_lshlrev_b32_e32 v20, 3, v3
	v_lshl_add_u32 v25, v3, 4, 0
	v_cmp_lt_u32_e64 s[4:5], s3, v23
	s_movk_i32 s3, 0x84
	v_mul_u32_u24_e32 v3, 0x90, v29
	s_movk_i32 s8, 0x1ff
	s_movk_i32 s10, 0x220
	s_movk_i32 s12, 0x300
	v_mul_u32_u24_e32 v4, 0x90, v48
	v_mul_u32_u24_e32 v6, 0x90, v1
	v_cmp_gt_u32_e64 s[28:29], v7, v5
	v_or_b32_e32 v7, 0x83, v32
	v_mad_u32_u24 v49, v1, s34, v2
	v_mbcnt_lo_u32_b32 v2, -1, 0
	v_cmp_gt_u32_e64 s[0:1], s0, v23
	s_mov_b32 s63, 0
	v_cmp_gt_u32_e64 s[6:7], s3, v23
	v_lshl_add_u32 v27, v23, 1, 0
	s_movk_i32 s3, 0x90
	v_cmp_lt_u32_e64 s[8:9], s8, v143
	v_cmp_gt_u32_e64 s[10:11], s10, v143
	v_cmp_gt_u32_e64 s[12:13], s12, v143
	v_mul_u32_u24_e32 v42, 0x90, v33
	v_mul_u32_u24_e32 v45, 0x90, v44
	v_cmp_gt_u32_e64 s[18:19], 4, v1
	v_cmp_gt_u32_e64 s[20:21], v32, v1
	v_cmp_lt_u32_e64 s[22:23], v32, v1
	v_cmp_gt_u32_e64 s[30:31], v7, v5
	v_lshl_add_u64 v[34:35], s[44:45], 0, v[18:19]
	s_lshl_b32 s42, s2, 5
	s_lshl_b32 s43, s74, 5
	v_add_u32_e32 v50, v25, v3
	v_add_u32_e32 v51, v30, v6
	s_mov_b32 s58, 0xff800000
	v_add_u32_e32 v52, v25, v4
	v_lshlrev_b32_e32 v18, 1, v18
	v_lshlrev_b32_e32 v36, 2, v20
	v_mbcnt_hi_u32_b32 v53, -1, v2
	v_mov_b32_e32 v54, 0xff800000
	s_mov_b32 s59, s2
	s_mov_b32 s60, s2
	v_readfirstlane_b32 s98, v143
	s_lshr_b32 s98, s98, 8
	s_cmp_lg_u32 s98, 0
	s_cbranch_scc0 .Lprio_att_done
	s_setprio 1
.Lprio_att_done:
	s_branch .LBB0_1113

.LBB0_1179:
	s_setprio 0
	s_cmp_gt_i32 s73, 11
	s_cselect_b64 s[0:1], -1, 0
	s_and_b64 s[4:5], s[56:57], s[0:1]
	s_andn2_b64 vcc, exec, s[4:5]
	s_cbranch_vccnz .LBB0_1243
	s_cmp_gt_i32 s72, -1
	s_mov_b64 s[4:5], -1
	s_cbranch_scc0 .LBB0_1230
	s_waitcnt vmcnt(0)
	v_cmp_eq_u32_e32 vcc, 0, v143
	s_waitcnt vmcnt(0) lgkmcnt(0)
	s_barrier
	s_and_saveexec_b64 s[4:5], vcc
	s_cbranch_execz .LBB0_1229
	s_mov_b32 s98, 9
	s_branch .Lsbar
	v_readlane_b32 s3, v242, 11
	s_waitcnt vmcnt(0) expcnt(0) lgkmcnt(0)
	s_nop 0
	v_mov_b32_e32 v1, s3
	ds_read_b32 v3, v1
	ds_read_b32 v1, v1 offset:4
	s_waitcnt lgkmcnt(1)
	v_cmp_ne_u32_e32 vcc, 0, v3
	s_cbranch_vccnz .LBB0_1197
	s_add_u32 s6, s70, 0x1000
	s_addc_u32 s7, s71, 0
	s_add_u32 s8, s70, 0x1100
	s_addc_u32 s9, s71, 0
	s_add_u32 s10, s70, 0x1200
	v_readlane_b32 s3, v242, 8
	s_addc_u32 s11, s71, 0
	s_mul_i32 s3, s75, s3
	s_add_u32 s12, s70, 0x1300
	s_mul_i32 s3, s3, s74
	s_addc_u32 s13, s71, 0
	s_mov_b32 s20, 1
	v_mov_b32_e32 v17, 0
	s_branch .LBB0_1185
